# XCD-aware tile ordering in the two FFN-up GEMM phases (each XCD keeps 12 A row-tiles L2-resident)
# baseline (speedup 1.0000x reference)
.LBB0_1035:
	s_and_b32 s2, s57, 7
	s_bfe_u32 s3, s57, 0x60003
	s_lshr_b32 s6, s57, 9
	s_lshl_b32 s6, s6, 6
	s_add_u32 s3, s3, s6
	s_mul_hi_u32 s6, s3, 0xaaaaaaab
	s_lshr_b32 s6, s6, 3
	s_mul_i32 s7, s6, 12
	s_sub_u32 s3, s3, s7
	s_mul_i32 s2, s2, 12
	s_add_u32 s2, s2, s3
	s_lshl_b32 s48, s2, 7
	s_lshl_b32 s49, s6, 7
	v_lshl_or_b32 v64, v183, 3, v191
	v_and_b32_e32 v65, 63, v64
	v_lshrrev_b32_e32 v66, 3, v65
	v_lshrrev_b32_e32 v67, 4, v65
	v_xor_b32_e32 v67, v67, v65
	v_and_b32_e32 v67, 7, v67
	v_lshlrev_b32_e32 v67, 4, v67
	s_movk_i32 s99, 0x800
	v_mad_u32_u24 v112, v66, s99, v67
	v_xor_b32_e32 v68, 64, v112
	v_add_u32_e32 v113, 0x3c00, v68
	v_add_u32_e32 v114, 0x7800, v112
	v_add_u32_e32 v115, 0xb400, v68
	v_add_u32_e32 v116, 0x10000, v112
	v_add_u32_e32 v117, 0x13c00, v68
	v_add_u32_e32 v118, 0x17800, v112
	v_add_u32_e32 v119, 0x1b400, v68
	v_and_b32_e32 v69, 31, v64
	v_bfe_u32 v70, v64, 5, 1
	v_bfe_u32 v71, v64, 1, 3
	v_xor_b32_e32 v71, v71, v70
	v_lshlrev_b32_e32 v71, 4, v71
	v_bfe_u32 v72, v64, 7, 1
	v_lshl_or_b32 v72, v72, 6, v69
	v_lshl_add_u32 v120, v72, 7, v71
	v_bfe_u32 v73, v64, 6, 1
	v_lshl_or_b32 v73, v73, 6, v69
	v_lshl_add_u32 v124, v73, 7, v71
	v_add_u32_e32 v124, 0x4000, v124
	v_xor_b32_e32 v121, 32, v120
	v_xor_b32_e32 v125, 32, v124
	v_xor_b32_e32 v122, 64, v120
	v_xor_b32_e32 v126, 64, v124
	v_xor_b32_e32 v123, 96, v120
	v_xor_b32_e32 v127, 96, v124
	v_lshrrev_b32_e32 v74, 6, v64
	s_nop 0
	v_readfirstlane_b32 s100, v74
	s_nop 3
	s_lshl_b32 s98, s100, 13
	s_mov_b32 s101, 0xb40000
	s_mov_b32 s99, s49
	s_cmp_lt_u32 s100, 2
	s_cmov_b32 s101, 0xb171900
	s_cmov_b32 s99, s48
	s_and_b32 s100, s100, 1
	s_lshl_b32 s100, s100, 6
	s_add_u32 s99, s99, s100
	s_mul_i32 s99, s99, 0x800
	s_add_u32 s99, s99, s101
	s_add_u32 s2, s90, s99
	s_addc_u32 s3, s91, 0
	s_add_u32 m0, s98, 0x0
	s_nop 0
	global_load_lds_dwordx4 v112, s[2:3] offset:0
	global_load_lds_dwordx4 v113, s[2:3] offset:1024
	global_load_lds_dwordx4 v114, s[2:3] offset:2048
	global_load_lds_dwordx4 v115, s[2:3] offset:3072
	s_add_u32 m0, s98, 0x1000
	s_nop 0
	global_load_lds_dwordx4 v116, s[2:3] offset:0
	global_load_lds_dwordx4 v117, s[2:3] offset:1024
	global_load_lds_dwordx4 v118, s[2:3] offset:2048
	global_load_lds_dwordx4 v119, s[2:3] offset:3072
	s_add_u32 s2, s2, 0x80
	s_addc_u32 s3, s3, 0
	s_add_u32 m0, s98, 0x8000
	s_nop 0
	global_load_lds_dwordx4 v112, s[2:3] offset:0
	global_load_lds_dwordx4 v113, s[2:3] offset:1024
	global_load_lds_dwordx4 v114, s[2:3] offset:2048
	global_load_lds_dwordx4 v115, s[2:3] offset:3072
	s_add_u32 m0, s98, 0x9000
	s_nop 0
	global_load_lds_dwordx4 v116, s[2:3] offset:0
	global_load_lds_dwordx4 v117, s[2:3] offset:1024
	global_load_lds_dwordx4 v118, s[2:3] offset:2048
	global_load_lds_dwordx4 v119, s[2:3] offset:3072
	s_add_u32 s2, s2, 0x80
	s_addc_u32 s3, s3, 0
	v_mov_b32_e32 v48, 0
	v_mov_b32_e32 v49, 0
	v_mov_b32_e32 v50, 0
	v_mov_b32_e32 v51, 0
	v_mov_b32_e32 v52, 0
	v_mov_b32_e32 v53, 0
	v_mov_b32_e32 v54, 0
	v_mov_b32_e32 v55, 0
	v_mov_b32_e32 v56, 0
	v_mov_b32_e32 v57, 0
	v_mov_b32_e32 v58, 0
	v_mov_b32_e32 v59, 0
	v_mov_b32_e32 v60, 0
	v_mov_b32_e32 v61, 0
	v_mov_b32_e32 v62, 0
	v_mov_b32_e32 v63, 0
	v_mov_b32_e32 v32, 0
	v_mov_b32_e32 v33, 0
	v_mov_b32_e32 v34, 0
	v_mov_b32_e32 v35, 0
	v_mov_b32_e32 v36, 0
	v_mov_b32_e32 v37, 0
	v_mov_b32_e32 v38, 0
	v_mov_b32_e32 v39, 0
	v_mov_b32_e32 v40, 0
	v_mov_b32_e32 v41, 0
	v_mov_b32_e32 v42, 0
	v_mov_b32_e32 v43, 0
	v_mov_b32_e32 v44, 0
	v_mov_b32_e32 v45, 0
	v_mov_b32_e32 v46, 0
	v_mov_b32_e32 v47, 0
	v_mov_b32_e32 v16, 0
	v_mov_b32_e32 v17, 0
	v_mov_b32_e32 v18, 0
	v_mov_b32_e32 v19, 0
	v_mov_b32_e32 v20, 0
	v_mov_b32_e32 v21, 0
	v_mov_b32_e32 v22, 0
	v_mov_b32_e32 v23, 0
	v_mov_b32_e32 v24, 0
	v_mov_b32_e32 v25, 0
	v_mov_b32_e32 v26, 0
	v_mov_b32_e32 v27, 0
	v_mov_b32_e32 v28, 0
	v_mov_b32_e32 v29, 0
	v_mov_b32_e32 v30, 0
	v_mov_b32_e32 v31, 0
	v_mov_b32_e32 v0, 0
	v_mov_b32_e32 v1, 0
	v_mov_b32_e32 v2, 0
	v_mov_b32_e32 v3, 0
	v_mov_b32_e32 v4, 0
	v_mov_b32_e32 v5, 0
	v_mov_b32_e32 v6, 0
	v_mov_b32_e32 v7, 0
	v_mov_b32_e32 v8, 0
	v_mov_b32_e32 v9, 0
	v_mov_b32_e32 v10, 0
	v_mov_b32_e32 v11, 0
	v_mov_b32_e32 v12, 0
	v_mov_b32_e32 v13, 0
	v_mov_b32_e32 v14, 0
	v_mov_b32_e32 v15, 0
	s_movk_i32 s6, 7
	s_waitcnt vmcnt(8)

.LBB0_2284:
	s_and_b32 s4, s47, 7
	s_bfe_u32 s5, s47, 0x60003
	s_lshr_b32 s6, s47, 9
	s_lshl_b32 s6, s6, 6
	s_add_u32 s5, s5, s6
	s_mul_hi_u32 s6, s5, 0xaaaaaaab
	s_lshr_b32 s6, s6, 3
	s_mul_i32 s7, s6, 12
	s_sub_u32 s5, s5, s7
	s_mul_i32 s4, s4, 12
	s_add_u32 s4, s4, s5
	s_lshl_b32 s48, s4, 7
	s_lshl_b32 s49, s6, 7
	v_lshl_or_b32 v64, v183, 3, v191
	v_and_b32_e32 v65, 63, v64
	v_lshrrev_b32_e32 v66, 3, v65
	v_lshrrev_b32_e32 v67, 4, v65
	v_xor_b32_e32 v67, v67, v65
	v_and_b32_e32 v67, 7, v67
	v_lshlrev_b32_e32 v67, 4, v67
	s_movk_i32 s99, 0x800
	v_mad_u32_u24 v112, v66, s99, v67
	v_xor_b32_e32 v68, 64, v112
	v_add_u32_e32 v113, 0x3c00, v68
	v_add_u32_e32 v114, 0x7800, v112
	v_add_u32_e32 v115, 0xb400, v68
	v_add_u32_e32 v116, 0x10000, v112
	v_add_u32_e32 v117, 0x13c00, v68
	v_add_u32_e32 v118, 0x17800, v112
	v_add_u32_e32 v119, 0x1b400, v68
	v_and_b32_e32 v69, 31, v64
	v_bfe_u32 v70, v64, 5, 1
	v_bfe_u32 v71, v64, 1, 3
	v_xor_b32_e32 v71, v71, v70
	v_lshlrev_b32_e32 v71, 4, v71
	v_bfe_u32 v72, v64, 7, 1
	v_lshl_or_b32 v72, v72, 6, v69
	v_lshl_add_u32 v120, v72, 7, v71
	v_bfe_u32 v73, v64, 6, 1
	v_lshl_or_b32 v73, v73, 6, v69
	v_lshl_add_u32 v124, v73, 7, v71
	v_add_u32_e32 v124, 0x4000, v124
	v_xor_b32_e32 v121, 32, v120
	v_xor_b32_e32 v125, 32, v124
	v_xor_b32_e32 v122, 64, v120
	v_xor_b32_e32 v126, 64, v124
	v_xor_b32_e32 v123, 96, v120
	v_xor_b32_e32 v127, 96, v124
	v_lshrrev_b32_e32 v74, 6, v64
	s_nop 0
	v_readfirstlane_b32 s100, v74
	s_nop 3
	s_lshl_b32 s98, s100, 13
	s_mov_b32 s101, 0x1640000
	s_mov_b32 s99, s49
	s_cmp_lt_u32 s100, 2
	s_cmov_b32 s101, 0xb171900
	s_cmov_b32 s99, s48
	s_and_b32 s100, s100, 1
	s_lshl_b32 s100, s100, 6
	s_add_u32 s99, s99, s100
	s_mul_i32 s99, s99, 0x800
	s_add_u32 s99, s99, s101
	s_add_u32 s4, s90, s99
	s_addc_u32 s5, s91, 0
	s_add_u32 m0, s98, 0x0
	s_nop 0
	global_load_lds_dwordx4 v112, s[4:5] offset:0
	global_load_lds_dwordx4 v113, s[4:5] offset:1024
	global_load_lds_dwordx4 v114, s[4:5] offset:2048
	global_load_lds_dwordx4 v115, s[4:5] offset:3072
	s_add_u32 m0, s98, 0x1000
	s_nop 0
	global_load_lds_dwordx4 v116, s[4:5] offset:0
	global_load_lds_dwordx4 v117, s[4:5] offset:1024
	global_load_lds_dwordx4 v118, s[4:5] offset:2048
	global_load_lds_dwordx4 v119, s[4:5] offset:3072
	s_add_u32 s4, s4, 0x80
	s_addc_u32 s5, s5, 0
	s_add_u32 m0, s98, 0x8000
	s_nop 0
	global_load_lds_dwordx4 v112, s[4:5] offset:0
	global_load_lds_dwordx4 v113, s[4:5] offset:1024
	global_load_lds_dwordx4 v114, s[4:5] offset:2048
	global_load_lds_dwordx4 v115, s[4:5] offset:3072
	s_add_u32 m0, s98, 0x9000
	s_nop 0
	global_load_lds_dwordx4 v116, s[4:5] offset:0
	global_load_lds_dwordx4 v117, s[4:5] offset:1024
	global_load_lds_dwordx4 v118, s[4:5] offset:2048
	global_load_lds_dwordx4 v119, s[4:5] offset:3072
	s_add_u32 s4, s4, 0x80
	s_addc_u32 s5, s5, 0
	v_mov_b32_e32 v48, 0
	v_mov_b32_e32 v49, 0
	v_mov_b32_e32 v50, 0
	v_mov_b32_e32 v51, 0
	v_mov_b32_e32 v52, 0
	v_mov_b32_e32 v53, 0
	v_mov_b32_e32 v54, 0
	v_mov_b32_e32 v55, 0
	v_mov_b32_e32 v56, 0
	v_mov_b32_e32 v57, 0
	v_mov_b32_e32 v58, 0
	v_mov_b32_e32 v59, 0
	v_mov_b32_e32 v60, 0
	v_mov_b32_e32 v61, 0
	v_mov_b32_e32 v62, 0
	v_mov_b32_e32 v63, 0
	v_mov_b32_e32 v32, 0
	v_mov_b32_e32 v33, 0
	v_mov_b32_e32 v34, 0
	v_mov_b32_e32 v35, 0
	v_mov_b32_e32 v36, 0
	v_mov_b32_e32 v37, 0
	v_mov_b32_e32 v38, 0
	v_mov_b32_e32 v39, 0
	v_mov_b32_e32 v40, 0
	v_mov_b32_e32 v41, 0
	v_mov_b32_e32 v42, 0
	v_mov_b32_e32 v43, 0
	v_mov_b32_e32 v44, 0
	v_mov_b32_e32 v45, 0
	v_mov_b32_e32 v46, 0
	v_mov_b32_e32 v47, 0
	v_mov_b32_e32 v16, 0
	v_mov_b32_e32 v17, 0
	v_mov_b32_e32 v18, 0
	v_mov_b32_e32 v19, 0
	v_mov_b32_e32 v20, 0
	v_mov_b32_e32 v21, 0
	v_mov_b32_e32 v22, 0
	v_mov_b32_e32 v23, 0
	v_mov_b32_e32 v24, 0
	v_mov_b32_e32 v25, 0
	v_mov_b32_e32 v26, 0
	v_mov_b32_e32 v27, 0
	v_mov_b32_e32 v28, 0
	v_mov_b32_e32 v29, 0
	v_mov_b32_e32 v30, 0
	v_mov_b32_e32 v31, 0
	v_mov_b32_e32 v0, 0
	v_mov_b32_e32 v1, 0
	v_mov_b32_e32 v2, 0
	v_mov_b32_e32 v3, 0
	v_mov_b32_e32 v4, 0
	v_mov_b32_e32 v5, 0
	v_mov_b32_e32 v6, 0
	v_mov_b32_e32 v7, 0
	v_mov_b32_e32 v8, 0
	v_mov_b32_e32 v9, 0
	v_mov_b32_e32 v10, 0
	v_mov_b32_e32 v11, 0
	v_mov_b32_e32 v12, 0
	v_mov_b32_e32 v13, 0
	v_mov_b32_e32 v14, 0
	v_mov_b32_e32 v15, 0
	s_movk_i32 s6, 7
	s_waitcnt vmcnt(8)
